# P0 row pass: 16-byte bf16 stores (each lane converts 8 consecutive floats) instead of 8-byte stores
# baseline (speedup 1.0000x reference)
; #define GAS __attribute__((address_space(1)))
; __device__ __forceinline__ unsigned pk2(float lo, float hi) { return pg8::cvt_pk_bf16(lo, hi); }
; __global__ void __launch_bounds__(NWAVES * 64, 2) mk_fwd(Args args) {
;     ...
;         for (int m = gw; m < T; m += NGW) {
;             const GAS f32x4* xr = (const GAS f32x4*)(x + (size_t)m * DM) + lane; f32x4 v[8]; float s = 0.f;
; #pragma unroll
;             for (int j = 0; j < 8; ++j) { v[j] = __builtin_nontemporal_load(&xr[64 * j]); s += (v[j].x * v[j].x + v[j].y * v[j].y) + (v[j].z * v[j].z + v[j].w * v[j].w); }
;             s = wave_sum(s);
;             if (lane == 0) { const float iv = 1.0f / sqrtf(s * (1.0f / DM) + EPS); inv0[m] = iv; }
;             GAS unsigned long long* o8 = (GAS unsigned long long*)(xb + (size_t)m * DM) + lane;
; #pragma unroll
;             for (int j = 0; j < 8; ++j) o8[64 * j] = (unsigned long long)pk2(v[j].x, v[j].y) | ((unsigned long long)pk2(v[j].z, v[j].w) << 32);
;         }
.LBB0_11:
	s_or_b64 exec, exec, s[4:5]
	s_lshr_b32 s49, s48, 6
	s_lshl_b32 s51, s2, 3
	s_load_dwordx16 s[8:23], s[0:1], 0x0
	s_lshl_b32 s96, s3, 3
	s_add_i32 s38, s49, s51
	s_cmpk_lt_i32 s38, 0x4000
	s_cselect_b64 s[0:1], -1, 0
	v_writelane_b32 v254, s0, 8
	v_and_b32_e32 v1, 63, v0
	s_cmpk_gt_i32 s38, 0x3fff
	v_writelane_b32 v254, s1, 9
	v_mbcnt_lo_u32_b32 v253, -1, 0
	s_cbranch_scc1 .LBB0_16
	v_mbcnt_hi_u32_b32 v2, -1, v253
	v_and_b32_e32 v3, 64, v2
	v_add_u32_e32 v3, 64, v3
	v_xor_b32_e32 v4, 1, v2
	v_cmp_lt_i32_e32 vcc, v4, v3
	s_ashr_i32 s39, s38, 31
	s_lshl_b64 s[4:5], s[38:39], 2
	v_cndmask_b32_e32 v4, v2, v4, vcc
	v_lshlrev_b32_e32 v40, 2, v4
	v_xor_b32_e32 v4, 2, v2
	v_cmp_lt_i32_e32 vcc, v4, v3
	s_add_u32 s28, s4, 0x100000
	s_addc_u32 s29, s5, 0
	v_cndmask_b32_e32 v4, v2, v4, vcc
	v_lshlrev_b32_e32 v41, 2, v4
	v_xor_b32_e32 v4, 4, v2
	v_cmp_lt_i32_e32 vcc, v4, v3
	s_ashr_i32 s97, s96, 31
	s_lshl_b64 s[4:5], s[38:39], 12
	v_cndmask_b32_e32 v4, v2, v4, vcc
	v_lshlrev_b32_e32 v42, 2, v4
	v_xor_b32_e32 v4, 8, v2
	v_cmp_lt_i32_e32 vcc, v4, v3
	s_lshl_b64 s[6:7], s[96:97], 2
	v_lshl_or_b32 v34, v1, 4, s4
	v_cndmask_b32_e32 v4, v2, v4, vcc
	v_lshlrev_b32_e32 v43, 2, v4
	v_xor_b32_e32 v4, 16, v2
	v_cmp_lt_i32_e32 vcc, v4, v3
	v_mov_b32_e32 v35, s5
	s_lshl_b64 s[24:25], s[96:97], 12
	v_cndmask_b32_e32 v4, v2, v4, vcc
	v_lshlrev_b32_e32 v44, 2, v4
	v_xor_b32_e32 v4, 32, v2
	s_lshl_b64 s[4:5], s[38:39], 13
	v_cmp_lt_i32_e32 vcc, v4, v3
	s_waitcnt lgkmcnt(0)
	s_add_u32 s4, s8, s4
	v_lshlrev_b32_e32 v36, 5, v1
	v_cndmask_b32_e32 v2, v2, v4, vcc
	v_mov_b32_e32 v37, 0
	s_addc_u32 s5, s9, s5
	v_lshlrev_b32_e32 v45, 2, v2
	v_lshl_add_u64 v[2:3], s[4:5], 0, v[36:37]
	s_mov_b64 s[4:5], 0x1c00
	v_cmp_eq_u32_e64 s[0:1], 0, v1
	v_lshl_add_u64 v[38:39], v[2:3], 0, s[4:5]
	s_lshl_b64 s[8:9], s[96:97], 13
	v_mov_b32_e32 v36, 0x358637bd
	s_mov_b32 s30, 0xf800000
	v_mov_b32_e32 v46, 0x260
	s_mov_b32 s31, s38
	s_branch .LBB0_14
.LBB0_13:
	s_or_b64 exec, exec, s[26:27]
	s_waitcnt lgkmcnt(0)
	v_lshl_add_u64 v[48:49], s[94:95], 0, v[34:35]
	v_cvt_pk_bf16_f32 v30, v30, v31
	v_cvt_pk_bf16_f32 v31, v32, v33
	v_add_co_u32_e32 v50, vcc, 0xa400000, v48
	s_add_i32 s31, s31, s96
	s_nop 0
	v_addc_co_u32_e32 v51, vcc, 0, v49, vcc
	v_cvt_pk_bf16_f32 v32, v26, v27
	v_cvt_pk_bf16_f32 v33, v28, v29
	global_store_dwordx4 v[50:51], v[30:33], off
	v_cvt_pk_bf16_f32 v22, v22, v23
	v_cvt_pk_bf16_f32 v23, v24, v25
	v_cvt_pk_bf16_f32 v24, v18, v19
	v_cvt_pk_bf16_f32 v25, v20, v21
	global_store_dwordx4 v[50:51], v[22:25], off offset:1024
	v_cvt_pk_bf16_f32 v2, v2, v3
	v_cvt_pk_bf16_f32 v3, v4, v5
	s_add_u32 s28, s28, s6
	v_cvt_pk_bf16_f32 v4, v6, v7
	v_cvt_pk_bf16_f32 v5, v8, v9
	global_store_dwordx4 v[50:51], v[2:5], off offset:2048
	s_addc_u32 s29, s29, s7
	v_cvt_pk_bf16_f32 v10, v10, v11
	v_cvt_pk_bf16_f32 v11, v12, v13
	v_lshl_add_u64 v[34:35], v[34:35], 0, s[24:25]
	s_cmpk_gt_i32 s31, 0x3fff
	v_lshl_add_u64 v[38:39], v[38:39], 0, s[8:9]
	v_cvt_pk_bf16_f32 v12, v14, v15
	v_cvt_pk_bf16_f32 v13, v16, v17
	global_store_dwordx4 v[50:51], v[10:13], off offset:3072
	s_cbranch_scc1 .LBB0_16
.LBB0_14:
	v_add_co_u32_e32 v48, vcc, 0xfffff000, v38
	global_load_dwordx4 v[2:5], v[38:39], off offset:-3072 nt
	global_load_dwordx4 v[6:9], v[38:39], off offset:-3056 nt
	global_load_dwordx4 v[10:13], v[38:39], off offset:-1024 nt
	global_load_dwordx4 v[14:17], v[38:39], off offset:-1008 nt
	v_addc_co_u32_e32 v49, vcc, -1, v39, vcc
	global_load_dwordx4 v[30:33], v[48:49], off offset:-3072 nt
	global_load_dwordx4 v[26:29], v[48:49], off offset:-3056 nt
	global_load_dwordx4 v[22:25], v[48:49], off offset:-1024 nt
	global_load_dwordx4 v[18:21], v[48:49], off offset:-1008 nt
	s_waitcnt vmcnt(7)
	v_mul_f32_e32 v47, v3, v3
	v_mul_f32_e32 v48, v5, v5
	s_waitcnt vmcnt(6)
	v_mul_f32_e32 v49, v7, v7
	v_mul_f32_e32 v50, v9, v9
	s_waitcnt vmcnt(5)
	v_mul_f32_e32 v51, v11, v11
	v_mul_f32_e32 v52, v13, v13
	s_waitcnt vmcnt(3)
	v_mul_f32_e32 v55, v31, v31
	v_mul_f32_e32 v56, v33, v33
	s_waitcnt vmcnt(2)
	v_mul_f32_e32 v57, v27, v27
	v_mul_f32_e32 v58, v29, v29
	v_fmac_f32_e32 v47, v2, v2
	v_fmac_f32_e32 v48, v4, v4
	v_fmac_f32_e32 v49, v6, v6
	v_fmac_f32_e32 v50, v8, v8
	v_fmac_f32_e32 v51, v10, v10
	v_fmac_f32_e32 v52, v12, v12
	s_waitcnt vmcnt(1)
	v_mul_f32_e32 v59, v23, v23
	v_mul_f32_e32 v60, v25, v25
	v_fmac_f32_e32 v55, v30, v30
	v_fmac_f32_e32 v56, v32, v32
	v_fmac_f32_e32 v57, v26, v26
	v_fmac_f32_e32 v58, v28, v28
	s_waitcnt vmcnt(0)
	v_mul_f32_e32 v61, v19, v19
	v_mul_f32_e32 v62, v21, v21
	v_add_f32_e32 v47, v47, v48
	v_add_f32_e32 v48, v49, v50
	v_add_f32_e32 v49, v51, v52
	v_fmac_f32_e32 v59, v22, v22
	v_fmac_f32_e32 v60, v24, v24
	v_add_f32_e32 v50, v55, v56
	v_add_f32_e32 v51, v57, v58
	v_fmac_f32_e32 v61, v18, v18
	v_fmac_f32_e32 v62, v20, v20
	v_add_f32_e32 v52, v59, v60
	v_add_f32_e32 v50, v50, v51
	v_add_f32_e32 v55, v61, v62
	v_add_f32_e32 v50, v50, v52
	v_add_f32_e32 v50, v50, v55
	v_mul_f32_e32 v53, v15, v15
	v_mul_f32_e32 v54, v17, v17
	v_add_f32_e32 v47, v50, v47
	v_fmac_f32_e32 v53, v14, v14
	v_fmac_f32_e32 v54, v16, v16
	v_add_f32_e32 v47, v47, v48
	v_add_f32_e32 v47, v47, v49
	v_add_f32_e32 v48, v53, v54
	v_add_f32_e32 v47, v47, v48
	ds_bpermute_b32 v48, v40, v47
	s_waitcnt lgkmcnt(0)
	v_add_f32_e32 v47, v47, v48
	ds_bpermute_b32 v48, v41, v47
	s_waitcnt lgkmcnt(0)
	v_add_f32_e32 v47, v47, v48
	ds_bpermute_b32 v48, v42, v47
	s_waitcnt lgkmcnt(0)
	v_add_f32_e32 v47, v47, v48
	ds_bpermute_b32 v48, v43, v47
	s_waitcnt lgkmcnt(0)
	v_add_f32_e32 v47, v47, v48
	ds_bpermute_b32 v48, v44, v47
	s_waitcnt lgkmcnt(0)
	v_add_f32_e32 v47, v47, v48
	ds_bpermute_b32 v48, v45, v47
	s_and_saveexec_b64 s[26:27], s[0:1]
	s_cbranch_execz .LBB0_13
	s_waitcnt lgkmcnt(0)
	v_add_f32_e32 v47, v47, v48
	v_fmamk_f32 v47, v47, 0x3a000000, v36
	v_mul_f32_e32 v48, 0x4f800000, v47
	v_cmp_gt_f32_e32 vcc, s30, v47
	s_nop 1
	v_cndmask_b32_e32 v47, v47, v48, vcc
	v_sqrt_f32_e32 v48, v47
	s_nop 0
	v_add_u32_e32 v49, -1, v48
	v_fma_f32 v51, -v49, v48, v47
	v_add_u32_e32 v50, 1, v48
	v_cmp_ge_f32_e64 s[4:5], 0, v51
	s_nop 1
	v_cndmask_b32_e64 v49, v48, v49, s[4:5]
	v_fma_f32 v48, -v50, v48, v47
	v_cmp_lt_f32_e64 s[4:5], 0, v48
	s_nop 1
	v_cndmask_b32_e64 v48, v49, v50, s[4:5]
	v_mul_f32_e32 v49, 0x37800000, v48
	v_cndmask_b32_e32 v48, v48, v49, vcc
	v_cmp_class_f32_e32 vcc, v47, v46
	s_nop 1
	v_cndmask_b32_e32 v47, v48, v47, vcc
	v_div_scale_f32 v48, s[4:5], v47, v47, 1.0
	v_rcp_f32_e32 v49, v48
	s_add_u32 s4, s94, s28
	s_addc_u32 s5, s95, s29
	v_fma_f32 v50, -v48, v49, 1.0
	v_fmac_f32_e32 v49, v50, v49
	v_div_scale_f32 v50, vcc, 1.0, v47, 1.0
	v_mul_f32_e32 v51, v50, v49
	v_fma_f32 v52, -v48, v51, v50
	v_fmac_f32_e32 v51, v52, v49
	v_fma_f32 v48, -v48, v51, v50
	v_div_fmas_f32 v48, v48, v49, v51
	v_div_fixup_f32 v47, v48, v47, 1.0
	global_store_dword v37, v47, s[4:5]
	s_branch .LBB0_13
